# v6 + NORM_R loop-invariant mu loads hoisted out of the row loop + COMBINE split 4 ways by rows over all 256 workgroups (one active wave per SIMD)
# baseline (speedup 1.0000x reference)
.LBB0_120:
	s_andn2_b64 vcc, exec, s[0:1]
	s_cbranch_vccnz .LBB0_132
	v_readlane_b32 s0, v252, 10
	v_readlane_b32 s1, v252, 11
	s_mov_b64 s[10:11], -1
	s_cmpk_eq_u32 s50, 0x100
	s_cbranch_scc0 .Lmy_cmb_orig
	s_lshr_b32 s12, s53, 1
	s_and_b32 s0, s2, 3
	s_cmp_eq_u32 s12, s0
	s_cselect_b64 s[10:11], -1, 0
	s_branch .Lmy_cmb_go

.Lmy_cmb_go:
	s_load_dwordx4 s[4:7], s[48:49], 0x140
	s_waitcnt vmcnt(0)
	v_lshlrev_b32_e32 v34, 3, v240
	v_ashrrev_i32_e32 v35, 31, v34
	v_lshlrev_b64 v[2:3], 2, v[34:35]
	s_waitcnt lgkmcnt(0)
	s_mov_b64 s[4:5], 0x4d00000
	s_add_u32 s0, s6, 0x100000
	s_addc_u32 s1, s7, 0
	v_lshl_add_u64 v[36:37], s[0:1], 0, v[2:3]
	v_lshl_add_u64 v[2:3], s[6:7], 0, v[2:3]
	v_lshl_add_u64 v[38:39], v[2:3], 0, s[4:5]
	v_lshlrev_b32_e32 v2, 5, v240
	v_add_u32_e32 v0, 0, v2
	v_and_b32_e32 v2, 0xffffff00, v2
	v_add_u32_e32 v40, 0, v2
	v_and_b32_e32 v2, 7, v240
	v_readlane_b32 s4, v254, 27
	s_nop 1
	v_lshl_add_u32 v41, v2, 5, s4
	s_mov_b32 s4, s2
	s_cmpk_eq_u32 s50, 0x100
	s_cbranch_scc0 .Lmy_cmb_s4
	s_lshr_b32 s4, s2, 2
.Lmy_cmb_s4:
	s_branch .LBB0_124
.LBB0_123:
	s_waitcnt lgkmcnt(0)
	s_barrier
	s_add_i32 s4, s4, s50
	s_cmp_gt_i32 s4, 63
	s_cbranch_scc1 .LBB0_132

.LBB0_126:
	s_or_b32 s14, s5, s6
	s_ashr_i32 s15, s14, 31
	s_lshl_b64 s[8:9], s[14:15], 14
	v_lshl_add_u64 v[10:11], v[38:39], 0, s[8:9]
	s_andn2_b64 vcc, exec, s[10:11]
	s_cbranch_vccnz .Lmy_cmb_nost
	s_waitcnt vmcnt(5)
	global_store_dwordx4 v[10:11], v[30:33], off
	s_waitcnt vmcnt(5)
	global_store_dwordx4 v[10:11], v[26:29], off offset:16
	s_branch .Lmy_cmb_stdone

.Lmy_cmb_stdone:
	s_cmp_eq_u32 s5, 15
	s_cbranch_scc1 .LBB0_125
	s_waitcnt vmcnt(3)
	v_mov_b64_e32 v[10:11], v[22:23]
	s_waitcnt vmcnt(2)
	v_mov_b64_e32 v[14:15], v[18:19]
	s_cmp_eq_u32 s5, 14
	v_mov_b64_e32 v[12:13], v[24:25]
	v_mov_b64_e32 v[16:17], v[20:21]
	ds_write_b128 v0, v[30:33]
	ds_write_b128 v0, v[26:29] offset:16
	ds_write_b128 v0, v[2:5] offset:16384
	ds_write_b128 v0, v[6:9] offset:16400
	s_cbranch_scc1 .LBB0_129
	s_lshl_b64 s[8:9], s[14:15], 15
	s_add_u32 s8, s0, s8
	s_addc_u32 s9, s1, s9
	v_lshl_add_u64 v[2:3], v[34:35], 2, s[8:9]
	v_add_co_u32_e32 v4, vcc, 0xc000, v2
	s_mov_b64 s[8:9], 0x8000
	s_nop 0
	v_addc_co_u32_e32 v5, vcc, 0, v3, vcc
	v_lshl_add_u64 v[10:11], v[2:3], 0, s[8:9]
	s_mov_b64 s[8:9], 0xc000
	v_add_co_u32_e32 v8, vcc, 0x8000, v2
	v_lshl_add_u64 v[6:7], v[2:3], 0, s[8:9]
	s_nop 0
	v_addc_co_u32_e32 v9, vcc, 0, v3, vcc
	global_load_dwordx4 v[2:5], v[4:5], off
	s_nop 0
	global_load_dwordx4 v[14:17], v[8:9], off
	s_nop 0
	global_load_dwordx4 v[6:9], v[6:7], off offset:16
	s_nop 0
	global_load_dwordx4 v[10:13], v[10:11], off offset:16
.LBB0_129:
	s_waitcnt lgkmcnt(0)
	s_barrier
	s_mov_b32 s7, 0
	v_mov_b32_e32 v26, v41
	s_andn2_b64 vcc, exec, s[10:11]
	s_cbranch_vccnz .Lmy_cmb_skiploop

.Lmy_cmb_skiploop:
	s_waitcnt lgkmcnt(0)
	s_barrier
	v_mov_b32_e32 v29, v25
	v_mov_b32_e32 v28, v24
	v_mov_b32_e32 v27, v23
	v_mov_b32_e32 v26, v22
	v_mov_b32_e32 v33, v21
	v_mov_b32_e32 v32, v20
	v_mov_b32_e32 v31, v19
	v_mov_b32_e32 v30, v18
	s_waitcnt vmcnt(2)
	v_mov_b64_e32 v[20:21], v[16:17]
	s_waitcnt vmcnt(0)
	v_mov_b64_e32 v[24:25], v[12:13]
	v_mov_b64_e32 v[18:19], v[14:15]
	v_mov_b64_e32 v[22:23], v[10:11]
	s_branch .LBB0_125

.LBB0_564:
	s_cmpk_gt_i32 s22, 0x2fff
	s_cbranch_scc1 .LBB0_595
	v_and_b32_e32 v0, 64, v217
	v_add_u32_e32 v0, 64, v0
	s_waitcnt vmcnt(0)
	v_xor_b32_e32 v2, 1, v217
	v_cmp_lt_i32_e32 vcc, v2, v0
	s_load_dwordx2 s[0:1], s[48:49], 0x98
	v_mov_b32_e32 v3, v1
	v_cndmask_b32_e32 v2, v217, v2, vcc
	s_waitcnt vmcnt(0)
	v_lshlrev_b32_e32 v116, 2, v2
	v_xor_b32_e32 v2, 2, v217
	v_cmp_lt_i32_e32 vcc, v2, v0
	s_waitcnt lgkmcnt(0)
	s_add_u32 s4, s0, 0x1000
	s_addc_u32 s5, s1, 0
	v_cndmask_b32_e32 v2, v217, v2, vcc
	v_lshlrev_b32_e32 v117, 2, v2
	v_xor_b32_e32 v2, 4, v217
	v_cmp_lt_i32_e32 vcc, v2, v0
	s_add_u32 s8, s0, 0x2000
	s_addc_u32 s9, s1, 0
	v_cndmask_b32_e32 v2, v217, v2, vcc
	v_lshlrev_b32_e32 v118, 2, v2
	v_xor_b32_e32 v2, 8, v217
	v_cmp_lt_i32_e32 vcc, v2, v0
	s_ashr_i32 s23, s22, 31
	v_lshlrev_b32_e32 v84, 3, v194
	v_cndmask_b32_e32 v2, v217, v2, vcc
	v_lshlrev_b32_e32 v119, 2, v2
	v_xor_b32_e32 v2, 16, v217
	v_cmp_lt_i32_e32 vcc, v2, v0
	v_mov_b32_e32 v85, v1
	s_nop 0
	v_cndmask_b32_e32 v2, v217, v2, vcc
	v_lshlrev_b32_e32 v120, 2, v2
	v_xor_b32_e32 v2, 32, v217
	v_cmp_lt_i32_e32 vcc, v2, v0
	s_nop 1
	v_cndmask_b32_e32 v0, v217, v2, vcc
	v_lshlrev_b32_e32 v121, 2, v0
	v_lshlrev_b32_e32 v0, 4, v194
	v_or_b32_e32 v2, 0x400, v0
	v_lshl_add_u64 v[72:73], s[4:5], 0, v[2:3]
	v_lshl_add_u64 v[74:75], s[8:9], 0, v[2:3]
	v_or_b32_e32 v2, 0x800, v0
	v_lshl_add_u64 v[76:77], s[4:5], 0, v[2:3]
	v_lshl_add_u64 v[78:79], s[8:9], 0, v[2:3]
	v_or_b32_e32 v2, 0xc00, v0
	v_lshl_add_u64 v[70:71], s[8:9], 0, v[0:1]
	v_lshl_add_u64 v[82:83], s[8:9], 0, v[2:3]
	s_load_dwordx4 s[8:11], s[48:49], 0x140
	v_lshl_add_u64 v[66:67], s[0:1], 0, v[0:1]
	s_lshl_b64 s[0:1], s[22:23], 11
	v_lshl_add_u64 v[68:69], s[4:5], 0, v[0:1]
	v_lshl_add_u64 v[80:81], s[4:5], 0, v[2:3]
	s_waitcnt lgkmcnt(0)
	s_add_u32 s0, s10, s0
	s_addc_u32 s1, s11, s1
	s_lshl_b64 s[4:5], s[22:23], 12
	s_add_u32 s14, s10, s4
	s_addc_u32 s15, s11, s5
	s_add_u32 s4, s8, s4
	s_addc_u32 s5, s9, s5
	v_lshl_add_u64 v[2:3], s[4:5], 0, v[0:1]
	s_mov_b64 s[4:5], 0xc00
	v_lshl_add_u64 v[86:87], v[2:3], 0, s[4:5]
	v_lshlrev_b32_e32 v0, 4, v194
	global_load_dwordx4 v[130:133], v[66:67], off
	global_load_dwordx4 v[134:137], v[68:69], off
	global_load_dwordx4 v[138:141], v[70:71], off
	global_load_dwordx4 v[142:145], v[66:67], off offset:1024
	global_load_dwordx4 v[146:149], v[72:73], off
	global_load_dwordx4 v[150:153], v[74:75], off
	global_load_dwordx4 v[154:157], v[66:67], off offset:2048
	global_load_dwordx4 v[158:161], v[76:77], off
	global_load_dwordx4 v[162:165], v[78:79], off
	global_load_dwordx4 v[166:169], v[66:67], off offset:3072
	global_load_dwordx4 v[170:173], v[80:81], off
	global_load_dwordx4 v[174:177], v[82:83], off
	s_waitcnt vmcnt(0)
	s_mov_b32 s4, s22
	s_branch .LBB0_567
.LBB0_566:
	v_add_f32_e32 v34, v122, v123
	v_fmamk_f32 v34, v34, 0x3a800000, v213
	v_mul_f32_e32 v35, 0x4b800000, v34
	v_cmp_gt_f32_e32 vcc, s79, v34
	s_mov_b32 s5, 0x3500000
	v_lshl_add_u64 v[48:49], s[0:1], 0, v[84:85]
	v_cndmask_b32_e32 v34, v34, v35, vcc
	v_rsq_f32_e32 v34, v34
	v_pk_add_f32 v[90:91], v[90:91], v[108:109]
	v_pk_add_f32 v[88:89], v[88:89], v[106:107]
	s_add_i32 s4, s4, s70
	v_mul_f32_e32 v35, 0x45800000, v34
	v_cndmask_b32_e32 v34, v34, v35, vcc
	v_pk_mul_f32 v[26:27], v[26:27], v[34:35] op_sel_hi:[1,0]
	v_pk_mul_f32 v[28:29], v[28:29], v[34:35] op_sel_hi:[1,0]
	v_pk_fma_f32 v[30:31], v[102:103], v[26:27], v[30:31]
	v_lshl_add_u64 v[26:27], s[14:15], 0, v[84:85]
	v_pk_fma_f32 v[32:33], v[100:101], v[28:29], v[32:33]
	v_add_co_u32_e32 v36, vcc, s5, v26
	v_cvt_pk_bf16_f32 v28, v30, v31
	v_cvt_pk_bf16_f32 v29, v32, v33
	v_addc_co_u32_e32 v37, vcc, 0, v27, vcc
	global_store_dwordx2 v[36:37], v[28:29], off
	v_pk_add_f32 v[26:27], v[98:99], v[112:113]
	v_pk_add_f32 v[28:29], v[96:97], v[110:111]
	v_pk_fma_f32 v[38:39], v[26:27], 0.5, v[32:33] op_sel_hi:[1,0,1] neg_lo:[0,0,1] neg_hi:[0,0,1]
	v_pk_fma_f32 v[40:41], v[28:29], 0.5, v[30:31] op_sel_hi:[1,0,1] neg_lo:[0,0,1] neg_hi:[0,0,1]
	v_cvt_pk_bf16_f32 v27, v38, v39
	v_cvt_pk_bf16_f32 v26, v40, v41
	global_store_dwordx2 v[36:37], v[26:27], off offset:2048
	s_mov_b32 s5, 0xc500000
	v_add_co_u32_e32 v96, vcc, s5, v48
	s_mov_b32 s5, 0xdd00000
	s_nop 0
	v_addc_co_u32_e32 v97, vcc, 0, v49, vcc
	v_add_co_u32_e32 v98, vcc, s5, v48
	s_mov_b32 s5, 0xf500000
	s_nop 0
	v_addc_co_u32_e32 v99, vcc, 0, v49, vcc
	v_pk_mul_f32 v[14:15], v[14:15], v[34:35] op_sel_hi:[1,0]
	v_pk_mul_f32 v[16:17], v[16:17], v[34:35] op_sel_hi:[1,0]
	v_add_co_u32_e32 v48, vcc, s5, v48
	v_pk_fma_f32 v[24:25], v[54:55], v[16:17], v[24:25]
	v_pk_fma_f32 v[22:23], v[56:57], v[14:15], v[22:23]
	v_addc_co_u32_e32 v49, vcc, 0, v49, vcc
	v_pk_fma_f32 v[54:55], v[88:89], 0.5, v[24:25] op_sel_hi:[1,0,1] neg_lo:[0,0,1] neg_hi:[0,0,1]
	v_pk_fma_f32 v[56:57], v[90:91], 0.5, v[22:23] op_sel_hi:[1,0,1] neg_lo:[0,0,1] neg_hi:[0,0,1]
	v_cvt_pk_bf16_f32 v14, v22, v23
	v_cvt_pk_bf16_f32 v15, v24, v25
	v_cvt_pk_bf16_f32 v16, v56, v57
	v_cvt_pk_bf16_f32 v17, v54, v55
	v_pk_mul_f32 v[10:11], v[10:11], v[34:35] op_sel_hi:[1,0]
	v_pk_mul_f32 v[12:13], v[12:13], v[34:35] op_sel_hi:[1,0]
	v_pk_fma_f32 v[18:19], v[64:65], v[10:11], v[18:19]
	v_pk_fma_f32 v[20:21], v[62:63], v[12:13], v[20:21]
	v_cvt_pk_bf16_f32 v10, v18, v19
	v_cvt_pk_bf16_f32 v11, v20, v21
	v_pk_mul_f32 v[2:3], v[2:3], v[34:35] op_sel_hi:[1,0]
	v_pk_mul_f32 v[4:5], v[4:5], v[34:35] op_sel_hi:[1,0]
	v_pk_fma_f32 v[6:7], v[52:53], v[2:3], v[6:7]
	v_pk_fma_f32 v[8:9], v[50:51], v[4:5], v[8:9]
	v_cvt_pk_bf16_f32 v2, v6, v7
	v_cvt_pk_bf16_f32 v3, v8, v9
	v_readlane_b32 s8, v254, 5
	v_readlane_b32 s9, v254, 6
	s_add_u32 s0, s0, s8
	s_addc_u32 s1, s1, s9
	s_add_u32 s14, s14, s96
	s_addc_u32 s15, s15, s97
	s_cmpk_gt_i32 s4, 0x2fff
	v_lshl_add_u64 v[86:87], v[86:87], 0, s[96:97]
	v_mov_b32_e32 v26, v130
	v_mov_b32_e32 v27, v131
	v_mov_b32_e32 v28, v132
	v_mov_b32_e32 v29, v133
	v_pk_fma_f32 v[28:29], v[38:39], v[28:29], v[32:33]
	v_pk_fma_f32 v[26:27], v[40:41], v[26:27], v[30:31]
	s_nop 0
	v_cvt_pk_bf16_f32 v26, v26, v27
	v_cvt_pk_bf16_f32 v27, v28, v29
	global_store_dwordx2 v[96:97], v[26:27], off
	v_mov_b32_e32 v26, v134
	v_mov_b32_e32 v27, v135
	v_mov_b32_e32 v28, v136
	v_mov_b32_e32 v29, v137
	v_pk_fma_f32 v[28:29], v[38:39], v[28:29], v[32:33]
	v_pk_fma_f32 v[26:27], v[40:41], v[26:27], v[30:31]
	s_nop 0
	v_cvt_pk_bf16_f32 v26, v26, v27
	v_cvt_pk_bf16_f32 v27, v28, v29
	global_store_dwordx2 v[98:99], v[26:27], off
	v_mov_b32_e32 v26, v138
	v_mov_b32_e32 v27, v139
	v_mov_b32_e32 v28, v140
	v_mov_b32_e32 v29, v141
	v_pk_fma_f32 v[28:29], v[38:39], v[28:29], v[32:33]
	v_pk_fma_f32 v[26:27], v[40:41], v[26:27], v[30:31]
	s_nop 0
	v_cvt_pk_bf16_f32 v26, v26, v27
	v_cvt_pk_bf16_f32 v27, v28, v29
	global_store_dwordx2 v[48:49], v[26:27], off
	global_store_dwordx2 v[36:37], v[14:15], off offset:512
	global_store_dwordx2 v[36:37], v[16:17], off offset:2560
	v_pk_add_f32 v[26:27], v[94:95], v[104:105]
	v_pk_add_f32 v[28:29], v[92:93], v[46:47]
	v_pk_fma_f32 v[26:27], v[26:27], 0.5, v[18:19] op_sel_hi:[1,0,1] neg_lo:[0,0,1] neg_hi:[0,0,1]
	v_pk_fma_f32 v[28:29], v[28:29], 0.5, v[20:21] op_sel_hi:[1,0,1] neg_lo:[0,0,1] neg_hi:[0,0,1]
	v_cvt_pk_bf16_f32 v12, v26, v27
	v_cvt_pk_bf16_f32 v13, v28, v29
	v_mov_b32_e32 v14, v142
	v_mov_b32_e32 v15, v143
	v_mov_b32_e32 v16, v144
	v_mov_b32_e32 v17, v145
	v_pk_fma_f32 v[16:17], v[54:55], v[16:17], v[24:25]
	v_pk_fma_f32 v[14:15], v[56:57], v[14:15], v[22:23]
	s_nop 0
	v_cvt_pk_bf16_f32 v14, v14, v15
	v_cvt_pk_bf16_f32 v15, v16, v17
	global_store_dwordx2 v[96:97], v[14:15], off offset:512
	v_mov_b32_e32 v14, v146
	v_mov_b32_e32 v15, v147
	v_mov_b32_e32 v16, v148
	v_mov_b32_e32 v17, v149
	v_pk_fma_f32 v[16:17], v[54:55], v[16:17], v[24:25]
	v_pk_fma_f32 v[14:15], v[56:57], v[14:15], v[22:23]
	s_nop 0
	v_cvt_pk_bf16_f32 v14, v14, v15
	v_cvt_pk_bf16_f32 v15, v16, v17
	global_store_dwordx2 v[98:99], v[14:15], off offset:512
	v_mov_b32_e32 v14, v150
	v_mov_b32_e32 v15, v151
	v_mov_b32_e32 v16, v152
	v_mov_b32_e32 v17, v153
	v_pk_fma_f32 v[16:17], v[54:55], v[16:17], v[24:25]
	v_pk_fma_f32 v[14:15], v[56:57], v[14:15], v[22:23]
	s_nop 0
	v_cvt_pk_bf16_f32 v14, v14, v15
	v_cvt_pk_bf16_f32 v15, v16, v17
	global_store_dwordx2 v[48:49], v[14:15], off offset:512
	global_store_dwordx2 v[36:37], v[10:11], off offset:1024
	global_store_dwordx2 v[36:37], v[12:13], off offset:3072
	v_pk_add_f32 v[14:15], v[60:61], v[44:45]
	v_pk_add_f32 v[16:17], v[58:59], v[42:43]
	v_pk_fma_f32 v[14:15], v[14:15], 0.5, v[6:7] op_sel_hi:[1,0,1] neg_lo:[0,0,1] neg_hi:[0,0,1]
	v_pk_fma_f32 v[16:17], v[16:17], 0.5, v[8:9] op_sel_hi:[1,0,1] neg_lo:[0,0,1] neg_hi:[0,0,1]
	v_cvt_pk_bf16_f32 v4, v14, v15
	v_cvt_pk_bf16_f32 v5, v16, v17
	v_mov_b32_e32 v10, v154
	v_mov_b32_e32 v11, v155
	v_mov_b32_e32 v12, v156
	v_mov_b32_e32 v13, v157
	v_pk_fma_f32 v[12:13], v[28:29], v[12:13], v[20:21]
	v_pk_fma_f32 v[10:11], v[26:27], v[10:11], v[18:19]
	s_nop 0
	v_cvt_pk_bf16_f32 v10, v10, v11
	v_cvt_pk_bf16_f32 v11, v12, v13
	global_store_dwordx2 v[96:97], v[10:11], off offset:1024
	v_mov_b32_e32 v10, v158
	v_mov_b32_e32 v11, v159
	v_mov_b32_e32 v12, v160
	v_mov_b32_e32 v13, v161
	v_pk_fma_f32 v[12:13], v[28:29], v[12:13], v[20:21]
	v_pk_fma_f32 v[10:11], v[26:27], v[10:11], v[18:19]
	s_nop 0
	v_cvt_pk_bf16_f32 v10, v10, v11
	v_cvt_pk_bf16_f32 v11, v12, v13
	global_store_dwordx2 v[98:99], v[10:11], off offset:1024
	v_mov_b32_e32 v10, v162
	v_mov_b32_e32 v11, v163
	v_mov_b32_e32 v12, v164
	v_mov_b32_e32 v13, v165
	v_pk_fma_f32 v[12:13], v[28:29], v[12:13], v[20:21]
	v_pk_fma_f32 v[10:11], v[26:27], v[10:11], v[18:19]
	s_nop 0
	v_cvt_pk_bf16_f32 v10, v10, v11
	v_cvt_pk_bf16_f32 v11, v12, v13
	global_store_dwordx2 v[48:49], v[10:11], off offset:1024
	global_store_dwordx2 v[36:37], v[2:3], off offset:1536
	global_store_dwordx2 v[36:37], v[4:5], off offset:3584
	v_mov_b32_e32 v2, v166
	v_mov_b32_e32 v3, v167
	v_mov_b32_e32 v4, v168
	v_mov_b32_e32 v5, v169
	v_pk_fma_f32 v[4:5], v[16:17], v[4:5], v[8:9]
	v_pk_fma_f32 v[2:3], v[14:15], v[2:3], v[6:7]
	s_nop 0
	v_cvt_pk_bf16_f32 v2, v2, v3
	v_cvt_pk_bf16_f32 v3, v4, v5
	global_store_dwordx2 v[96:97], v[2:3], off offset:1536
	v_mov_b32_e32 v2, v170
	v_mov_b32_e32 v3, v171
	v_mov_b32_e32 v4, v172
	v_mov_b32_e32 v5, v173
	v_pk_fma_f32 v[4:5], v[16:17], v[4:5], v[8:9]
	v_pk_fma_f32 v[2:3], v[14:15], v[2:3], v[6:7]
	s_nop 0
	v_cvt_pk_bf16_f32 v2, v2, v3
	v_cvt_pk_bf16_f32 v3, v4, v5
	global_store_dwordx2 v[98:99], v[2:3], off offset:1536
	v_mov_b32_e32 v2, v174
	v_mov_b32_e32 v3, v175
	v_mov_b32_e32 v4, v176
	v_mov_b32_e32 v5, v177
	v_pk_fma_f32 v[4:5], v[16:17], v[4:5], v[8:9]
	v_pk_fma_f32 v[2:3], v[14:15], v[2:3], v[6:7]
	s_nop 0
	v_cvt_pk_bf16_f32 v2, v2, v3
	v_cvt_pk_bf16_f32 v3, v4, v5
	global_store_dwordx2 v[48:49], v[2:3], off offset:1536
	s_cbranch_scc1 .LBB0_595
